# indexer rank loop: v_readlane instead of ds_bpermute pairs (on top of DPP zero-init removal)
# baseline (speedup 1.0000x reference)
; __device__ __forceinline__ void indexer_phase(const bf16_t* PJ, float* rk, unsigned short* SEL, LAS unsigned char* lds) {
;     ...
;                     const unsigned myi = have ? cl[lane] : 0xffffffffu; const float myv = have ? __builtin_bit_cast(float, cl[64 + lane]) : -INFINITY;
;                     unsigned rank = 0;
;                     for (unsigned j2 = 0; j2 < cnt_eq; ++j2) { const float vj = __shfl(myv, (int)j2); const unsigned ij = __shfl(myi, (int)j2); rank += (vj > myv || (vj == myv && ij < myi)) ? 1u : 0u; }
.LBB0_1022:
	s_waitcnt lgkmcnt(0)
	v_readlane_b32 s3, v1, s1
	s_nop 1
	v_cmp_eq_f32_e64 s[26:27], s3, v1
	v_cmp_lt_f32_e64 s[24:25], v1, s3
	v_readlane_b32 s3, v0, s1
	s_add_i32 s1, s1, 1
	s_nop 0
	v_cmp_lt_u32_e64 s[28:29], s3, v0
	s_nop 0
	s_and_b64 s[26:27], s[26:27], s[28:29]
	s_or_b64 s[24:25], s[24:25], s[26:27]
	s_cmp_eq_u32 s95, s1
	v_addc_co_u32_e64 v3, s[24:25], 0, v3, s[24:25]
	s_cbranch_scc0 .LBB0_1022
